# layer-0 embed/rowstat only: four per-row chunk loads hoisted, 4-iteration loop unrolled with counted waits
# speedup vs baseline: 1.0625x; 1.0058x over previous
.LBB0_102:
	global_load_dwordx4 v[64:67], v[16:17], off offset:-8
	global_load_dwordx4 v[68:71], v[16:17], off offset:1016
	global_load_dwordx4 v[72:75], v[16:17], off offset:2040
	global_load_dwordx4 v[76:79], v[16:17], off offset:3064
	s_waitcnt lgkmcnt(0)
	v_add_u32_e32 v9, s4, v26
	s_mov_b64 s[12:13], 0x400
	s_addk_i32 s4, 0x2000
	v_lshl_add_u64 v[16:17], v[16:17], 0, s[12:13]
	s_mov_b64 s[12:13], 0x10000
	s_cmpk_eq_u32 s4, 0x8000
	s_waitcnt vmcnt(3)
	v_cvt_pk_bf16_f32 v50, v64, v65
	v_cvt_pk_bf16_f32 v51, v66, v67
	global_store_dwordx2 v[18:19], v[50:51], off offset:-4
	ds_read_b128 v[22:25], v9
	ds_read_b128 v[38:41], v9 offset:16
	ds_read_b128 v[42:45], v9 offset:32
	ds_read_b128 v[46:49], v9 offset:48
	v_lshlrev_b32_e32 v54, 16, v50
	v_and_b32_e32 v59, 0xffff0000, v50
	s_waitcnt lgkmcnt(3)
	v_pk_fma_f32 v[20:21], v[22:23], v[54:55], v[20:21] op_sel_hi:[1,0,1]
	v_mov_b32_e32 v60, v59
	s_waitcnt lgkmcnt(1)
	v_pk_fma_f32 v[42:43], v[42:43], v[60:61], v[20:21] op_sel_hi:[1,0,1]
	ds_read_b128 v[20:23], v9 offset:64
	v_lshlrev_b32_e32 v58, 16, v51
	v_and_b32_e32 v56, 0xffff0000, v51
	v_fmac_f32_e32 v4, v54, v54
	v_pk_mul_f32 v[50:51], v[58:59], v[58:59]
	v_pk_fma_f32 v[14:15], v[24:25], v[54:55], v[14:15] op_sel_hi:[1,0,1]
	v_add_f32_e32 v4, v4, v51
	v_pk_fma_f32 v[14:15], v[44:45], v[60:61], v[14:15] op_sel_hi:[1,0,1]
	v_add_f32_e32 v4, v50, v4
	ds_read_b128 v[50:53], v9 offset:96
	s_waitcnt lgkmcnt(1)
	v_pk_fma_f32 v[14:15], v[22:23], v[58:59], v[14:15] op_sel_hi:[1,0,1]
	ds_read_b128 v[22:25], v9 offset:80
	v_pk_fma_f32 v[20:21], v[20:21], v[58:59], v[42:43] op_sel_hi:[1,0,1]
	ds_read_b128 v[42:45], v9 offset:112
	v_pk_fma_f32 v[12:13], v[38:39], v[54:55], v[12:13] op_sel_hi:[1,0,1]
	v_pk_fma_f32 v[10:11], v[40:41], v[54:55], v[10:11] op_sel_hi:[1,0,1]
	v_pk_fma_f32 v[12:13], v[46:47], v[60:61], v[12:13] op_sel_hi:[1,0,1]
	v_pk_fma_f32 v[10:11], v[48:49], v[60:61], v[10:11] op_sel_hi:[1,0,1]
	s_waitcnt lgkmcnt(1)
	v_pk_fma_f32 v[12:13], v[22:23], v[58:59], v[12:13] op_sel_hi:[1,0,1]
	v_pk_fma_f32 v[10:11], v[24:25], v[58:59], v[10:11] op_sel_hi:[1,0,1]
	v_fmac_f32_e32 v4, v56, v56
	v_pk_fma_f32 v[20:21], v[50:51], v[56:57], v[20:21] op_sel_hi:[1,0,1]
	v_pk_fma_f32 v[14:15], v[52:53], v[56:57], v[14:15] op_sel_hi:[1,0,1]
	s_waitcnt lgkmcnt(0)
	v_pk_fma_f32 v[12:13], v[42:43], v[56:57], v[12:13] op_sel_hi:[1,0,1]
	v_pk_fma_f32 v[10:11], v[44:45], v[56:57], v[10:11] op_sel_hi:[1,0,1]
	v_lshl_add_u64 v[18:19], v[18:19], 0, s[12:13]
	s_waitcnt lgkmcnt(0)
	v_add_u32_e32 v9, s4, v26
	s_mov_b64 s[12:13], 0x400
	s_addk_i32 s4, 0x2000
	v_lshl_add_u64 v[16:17], v[16:17], 0, s[12:13]
	s_mov_b64 s[12:13], 0x10000
	s_cmpk_eq_u32 s4, 0x8000
	s_waitcnt vmcnt(3)
	v_cvt_pk_bf16_f32 v50, v68, v69
	v_cvt_pk_bf16_f32 v51, v70, v71
	global_store_dwordx2 v[18:19], v[50:51], off offset:-4
	ds_read_b128 v[22:25], v9
	ds_read_b128 v[38:41], v9 offset:16
	ds_read_b128 v[42:45], v9 offset:32
	ds_read_b128 v[46:49], v9 offset:48
	v_lshlrev_b32_e32 v54, 16, v50
	v_and_b32_e32 v59, 0xffff0000, v50
	s_waitcnt lgkmcnt(3)
	v_pk_fma_f32 v[20:21], v[22:23], v[54:55], v[20:21] op_sel_hi:[1,0,1]
	v_mov_b32_e32 v60, v59
	s_waitcnt lgkmcnt(1)
	v_pk_fma_f32 v[42:43], v[42:43], v[60:61], v[20:21] op_sel_hi:[1,0,1]
	ds_read_b128 v[20:23], v9 offset:64
	v_lshlrev_b32_e32 v58, 16, v51
	v_and_b32_e32 v56, 0xffff0000, v51
	v_fmac_f32_e32 v4, v54, v54
	v_pk_mul_f32 v[50:51], v[58:59], v[58:59]
	v_pk_fma_f32 v[14:15], v[24:25], v[54:55], v[14:15] op_sel_hi:[1,0,1]
	v_add_f32_e32 v4, v4, v51
	v_pk_fma_f32 v[14:15], v[44:45], v[60:61], v[14:15] op_sel_hi:[1,0,1]
	v_add_f32_e32 v4, v50, v4
	ds_read_b128 v[50:53], v9 offset:96
	s_waitcnt lgkmcnt(1)
	v_pk_fma_f32 v[14:15], v[22:23], v[58:59], v[14:15] op_sel_hi:[1,0,1]
	ds_read_b128 v[22:25], v9 offset:80
	v_pk_fma_f32 v[20:21], v[20:21], v[58:59], v[42:43] op_sel_hi:[1,0,1]
	ds_read_b128 v[42:45], v9 offset:112
	v_pk_fma_f32 v[12:13], v[38:39], v[54:55], v[12:13] op_sel_hi:[1,0,1]
	v_pk_fma_f32 v[10:11], v[40:41], v[54:55], v[10:11] op_sel_hi:[1,0,1]
	v_pk_fma_f32 v[12:13], v[46:47], v[60:61], v[12:13] op_sel_hi:[1,0,1]
	v_pk_fma_f32 v[10:11], v[48:49], v[60:61], v[10:11] op_sel_hi:[1,0,1]
	s_waitcnt lgkmcnt(1)
	v_pk_fma_f32 v[12:13], v[22:23], v[58:59], v[12:13] op_sel_hi:[1,0,1]
	v_pk_fma_f32 v[10:11], v[24:25], v[58:59], v[10:11] op_sel_hi:[1,0,1]
	v_fmac_f32_e32 v4, v56, v56
	v_pk_fma_f32 v[20:21], v[50:51], v[56:57], v[20:21] op_sel_hi:[1,0,1]
	v_pk_fma_f32 v[14:15], v[52:53], v[56:57], v[14:15] op_sel_hi:[1,0,1]
	s_waitcnt lgkmcnt(0)
	v_pk_fma_f32 v[12:13], v[42:43], v[56:57], v[12:13] op_sel_hi:[1,0,1]
	v_pk_fma_f32 v[10:11], v[44:45], v[56:57], v[10:11] op_sel_hi:[1,0,1]
	v_lshl_add_u64 v[18:19], v[18:19], 0, s[12:13]
	s_waitcnt lgkmcnt(0)
	v_add_u32_e32 v9, s4, v26
	s_mov_b64 s[12:13], 0x400
	s_addk_i32 s4, 0x2000
	v_lshl_add_u64 v[16:17], v[16:17], 0, s[12:13]
	s_mov_b64 s[12:13], 0x10000
	s_cmpk_eq_u32 s4, 0x8000
	s_waitcnt vmcnt(3)
	v_cvt_pk_bf16_f32 v50, v72, v73
	v_cvt_pk_bf16_f32 v51, v74, v75
	global_store_dwordx2 v[18:19], v[50:51], off offset:-4
	ds_read_b128 v[22:25], v9
	ds_read_b128 v[38:41], v9 offset:16
	ds_read_b128 v[42:45], v9 offset:32
	ds_read_b128 v[46:49], v9 offset:48
	v_lshlrev_b32_e32 v54, 16, v50
	v_and_b32_e32 v59, 0xffff0000, v50
	s_waitcnt lgkmcnt(3)
	v_pk_fma_f32 v[20:21], v[22:23], v[54:55], v[20:21] op_sel_hi:[1,0,1]
	v_mov_b32_e32 v60, v59
	s_waitcnt lgkmcnt(1)
	v_pk_fma_f32 v[42:43], v[42:43], v[60:61], v[20:21] op_sel_hi:[1,0,1]
	ds_read_b128 v[20:23], v9 offset:64
	v_lshlrev_b32_e32 v58, 16, v51
	v_and_b32_e32 v56, 0xffff0000, v51
	v_fmac_f32_e32 v4, v54, v54
	v_pk_mul_f32 v[50:51], v[58:59], v[58:59]
	v_pk_fma_f32 v[14:15], v[24:25], v[54:55], v[14:15] op_sel_hi:[1,0,1]
	v_add_f32_e32 v4, v4, v51
	v_pk_fma_f32 v[14:15], v[44:45], v[60:61], v[14:15] op_sel_hi:[1,0,1]
	v_add_f32_e32 v4, v50, v4
	ds_read_b128 v[50:53], v9 offset:96
	s_waitcnt lgkmcnt(1)
	v_pk_fma_f32 v[14:15], v[22:23], v[58:59], v[14:15] op_sel_hi:[1,0,1]
	ds_read_b128 v[22:25], v9 offset:80
	v_pk_fma_f32 v[20:21], v[20:21], v[58:59], v[42:43] op_sel_hi:[1,0,1]
	ds_read_b128 v[42:45], v9 offset:112
	v_pk_fma_f32 v[12:13], v[38:39], v[54:55], v[12:13] op_sel_hi:[1,0,1]
	v_pk_fma_f32 v[10:11], v[40:41], v[54:55], v[10:11] op_sel_hi:[1,0,1]
	v_pk_fma_f32 v[12:13], v[46:47], v[60:61], v[12:13] op_sel_hi:[1,0,1]
	v_pk_fma_f32 v[10:11], v[48:49], v[60:61], v[10:11] op_sel_hi:[1,0,1]
	s_waitcnt lgkmcnt(1)
	v_pk_fma_f32 v[12:13], v[22:23], v[58:59], v[12:13] op_sel_hi:[1,0,1]
	v_pk_fma_f32 v[10:11], v[24:25], v[58:59], v[10:11] op_sel_hi:[1,0,1]
	v_fmac_f32_e32 v4, v56, v56
	v_pk_fma_f32 v[20:21], v[50:51], v[56:57], v[20:21] op_sel_hi:[1,0,1]
	v_pk_fma_f32 v[14:15], v[52:53], v[56:57], v[14:15] op_sel_hi:[1,0,1]
	s_waitcnt lgkmcnt(0)
	v_pk_fma_f32 v[12:13], v[42:43], v[56:57], v[12:13] op_sel_hi:[1,0,1]
	v_pk_fma_f32 v[10:11], v[44:45], v[56:57], v[10:11] op_sel_hi:[1,0,1]
	v_lshl_add_u64 v[18:19], v[18:19], 0, s[12:13]
	s_waitcnt lgkmcnt(0)
	v_add_u32_e32 v9, s4, v26
	s_mov_b64 s[12:13], 0x400
	s_addk_i32 s4, 0x2000
	v_lshl_add_u64 v[16:17], v[16:17], 0, s[12:13]
	s_mov_b64 s[12:13], 0x10000
	s_cmpk_eq_u32 s4, 0x8000
	s_waitcnt vmcnt(3)
	v_cvt_pk_bf16_f32 v50, v76, v77
	v_cvt_pk_bf16_f32 v51, v78, v79
	global_store_dwordx2 v[18:19], v[50:51], off offset:-4
	ds_read_b128 v[22:25], v9
	ds_read_b128 v[38:41], v9 offset:16
	ds_read_b128 v[42:45], v9 offset:32
	ds_read_b128 v[46:49], v9 offset:48
	v_lshlrev_b32_e32 v54, 16, v50
	v_and_b32_e32 v59, 0xffff0000, v50
	s_waitcnt lgkmcnt(3)
	v_pk_fma_f32 v[20:21], v[22:23], v[54:55], v[20:21] op_sel_hi:[1,0,1]
	v_mov_b32_e32 v60, v59
	s_waitcnt lgkmcnt(1)
	v_pk_fma_f32 v[42:43], v[42:43], v[60:61], v[20:21] op_sel_hi:[1,0,1]
	ds_read_b128 v[20:23], v9 offset:64
	v_lshlrev_b32_e32 v58, 16, v51
	v_and_b32_e32 v56, 0xffff0000, v51
	v_fmac_f32_e32 v4, v54, v54
	v_pk_mul_f32 v[50:51], v[58:59], v[58:59]
	v_pk_fma_f32 v[14:15], v[24:25], v[54:55], v[14:15] op_sel_hi:[1,0,1]
	v_add_f32_e32 v4, v4, v51
	v_pk_fma_f32 v[14:15], v[44:45], v[60:61], v[14:15] op_sel_hi:[1,0,1]
	v_add_f32_e32 v4, v50, v4
	ds_read_b128 v[50:53], v9 offset:96
	s_waitcnt lgkmcnt(1)
	v_pk_fma_f32 v[14:15], v[22:23], v[58:59], v[14:15] op_sel_hi:[1,0,1]
	ds_read_b128 v[22:25], v9 offset:80
	v_pk_fma_f32 v[20:21], v[20:21], v[58:59], v[42:43] op_sel_hi:[1,0,1]
	ds_read_b128 v[42:45], v9 offset:112
	v_pk_fma_f32 v[12:13], v[38:39], v[54:55], v[12:13] op_sel_hi:[1,0,1]
	v_pk_fma_f32 v[10:11], v[40:41], v[54:55], v[10:11] op_sel_hi:[1,0,1]
	v_pk_fma_f32 v[12:13], v[46:47], v[60:61], v[12:13] op_sel_hi:[1,0,1]
	v_pk_fma_f32 v[10:11], v[48:49], v[60:61], v[10:11] op_sel_hi:[1,0,1]
	s_waitcnt lgkmcnt(1)
	v_pk_fma_f32 v[12:13], v[22:23], v[58:59], v[12:13] op_sel_hi:[1,0,1]
	v_pk_fma_f32 v[10:11], v[24:25], v[58:59], v[10:11] op_sel_hi:[1,0,1]
	v_fmac_f32_e32 v4, v56, v56
	v_pk_fma_f32 v[20:21], v[50:51], v[56:57], v[20:21] op_sel_hi:[1,0,1]
	v_pk_fma_f32 v[14:15], v[52:53], v[56:57], v[14:15] op_sel_hi:[1,0,1]
	s_waitcnt lgkmcnt(0)
	v_pk_fma_f32 v[12:13], v[42:43], v[56:57], v[12:13] op_sel_hi:[1,0,1]
	v_pk_fma_f32 v[10:11], v[44:45], v[56:57], v[10:11] op_sel_hi:[1,0,1]
	v_lshl_add_u64 v[18:19], v[18:19], 0, s[12:13]
	v_mov_b32_dpp v16, v20 quad_perm:[1,0,3,2] row_mask:0xf bank_mask:0xf bound_ctrl:1
	v_mov_b32_dpp v17, v21 quad_perm:[1,0,3,2] row_mask:0xf bank_mask:0xf bound_ctrl:1
	v_pk_add_f32 v[16:17], v[20:21], v[16:17]
	v_mov_b32_dpp v20, v14 quad_perm:[1,0,3,2] row_mask:0xf bank_mask:0xf bound_ctrl:1
	v_mov_b32_dpp v21, v15 quad_perm:[1,0,3,2] row_mask:0xf bank_mask:0xf bound_ctrl:1
	v_pk_add_f32 v[14:15], v[14:15], v[20:21]
	v_mov_b32_dpp v18, v16 quad_perm:[2,3,0,1] row_mask:0xf bank_mask:0xf bound_ctrl:1
	v_mov_b32_dpp v19, v17 quad_perm:[2,3,0,1] row_mask:0xf bank_mask:0xf bound_ctrl:1
	v_mov_b32_dpp v20, v14 quad_perm:[2,3,0,1] row_mask:0xf bank_mask:0xf bound_ctrl:1
	v_mov_b32_dpp v21, v15 quad_perm:[2,3,0,1] row_mask:0xf bank_mask:0xf bound_ctrl:1
	v_pk_add_f32 v[16:17], v[16:17], v[18:19]
	v_pk_add_f32 v[14:15], v[14:15], v[20:21]
	v_mov_b32_dpp v24, v10 quad_perm:[1,0,3,2] row_mask:0xf bank_mask:0xf bound_ctrl:1
	v_mov_b32_dpp v18, v16 row_half_mirror row_mask:0xf bank_mask:0xf bound_ctrl:1
	v_mov_b32_dpp v19, v17 row_half_mirror row_mask:0xf bank_mask:0xf bound_ctrl:1
	v_mov_b32_dpp v20, v14 row_half_mirror row_mask:0xf bank_mask:0xf bound_ctrl:1
	v_mov_b32_dpp v21, v15 row_half_mirror row_mask:0xf bank_mask:0xf bound_ctrl:1
	v_pk_add_f32 v[16:17], v[16:17], v[18:19]
	v_pk_add_f32 v[14:15], v[14:15], v[20:21]
	v_mov_b32_dpp v25, v11 quad_perm:[1,0,3,2] row_mask:0xf bank_mask:0xf bound_ctrl:1
	v_mov_b32_dpp v18, v16 row_mirror row_mask:0xf bank_mask:0xf bound_ctrl:1
	v_mov_b32_dpp v19, v17 row_mirror row_mask:0xf bank_mask:0xf bound_ctrl:1
	v_mov_b32_dpp v20, v14 row_mirror row_mask:0xf bank_mask:0xf bound_ctrl:1
	v_mov_b32_dpp v21, v15 row_mirror row_mask:0xf bank_mask:0xf bound_ctrl:1
	v_pk_add_f32 v[16:17], v[16:17], v[18:19]
	v_pk_add_f32 v[20:21], v[14:15], v[20:21]
	ds_bpermute_b32 v18, v33, v16
	ds_bpermute_b32 v19, v33, v17
	ds_bpermute_b32 v22, v33, v20
	ds_bpermute_b32 v23, v33, v21
	v_pk_add_f32 v[10:11], v[10:11], v[24:25]
	v_add_f32_dpp v4, v4, v4 quad_perm:[1,0,3,2] row_mask:0xf bank_mask:0xf bound_ctrl:1
	s_waitcnt lgkmcnt(2)
	v_pk_add_f32 v[14:15], v[16:17], v[18:19]
	v_mov_b32_dpp v24, v10 quad_perm:[2,3,0,1] row_mask:0xf bank_mask:0xf bound_ctrl:1
	s_waitcnt lgkmcnt(0)
	v_pk_add_f32 v[18:19], v[20:21], v[22:23]
	v_mov_b32_dpp v22, v12 quad_perm:[1,0,3,2] row_mask:0xf bank_mask:0xf bound_ctrl:1
	v_mov_b32_dpp v23, v13 quad_perm:[1,0,3,2] row_mask:0xf bank_mask:0xf bound_ctrl:1
	v_pk_add_f32 v[12:13], v[12:13], v[22:23]
	v_mov_b32_dpp v25, v11 quad_perm:[2,3,0,1] row_mask:0xf bank_mask:0xf bound_ctrl:1
	v_pk_add_f32 v[10:11], v[10:11], v[24:25]
	v_mov_b32_dpp v22, v12 quad_perm:[2,3,0,1] row_mask:0xf bank_mask:0xf bound_ctrl:1
	v_mov_b32_dpp v23, v13 quad_perm:[2,3,0,1] row_mask:0xf bank_mask:0xf bound_ctrl:1
	v_pk_add_f32 v[12:13], v[12:13], v[22:23]
	v_mov_b32_dpp v24, v10 row_half_mirror row_mask:0xf bank_mask:0xf bound_ctrl:1
	v_mov_b32_dpp v25, v11 row_half_mirror row_mask:0xf bank_mask:0xf bound_ctrl:1
	v_mov_b32_dpp v22, v12 row_half_mirror row_mask:0xf bank_mask:0xf bound_ctrl:1
	v_mov_b32_dpp v23, v13 row_half_mirror row_mask:0xf bank_mask:0xf bound_ctrl:1
	v_add_f32_dpp v4, v4, v4 quad_perm:[2,3,0,1] row_mask:0xf bank_mask:0xf bound_ctrl:1
	v_pk_add_f32 v[12:13], v[12:13], v[22:23]
	v_pk_add_f32 v[10:11], v[10:11], v[24:25]
	v_add_f32_dpp v4, v4, v4 row_half_mirror row_mask:0xf bank_mask:0xf bound_ctrl:1
	v_mov_b32_dpp v22, v12 row_mirror row_mask:0xf bank_mask:0xf bound_ctrl:1
	v_mov_b32_dpp v23, v13 row_mirror row_mask:0xf bank_mask:0xf bound_ctrl:1
	v_mov_b32_dpp v24, v10 row_mirror row_mask:0xf bank_mask:0xf bound_ctrl:1
	v_mov_b32_dpp v25, v11 row_mirror row_mask:0xf bank_mask:0xf bound_ctrl:1
	v_add_f32_dpp v4, v4, v4 row_mirror row_mask:0xf bank_mask:0xf bound_ctrl:1
	v_pk_add_f32 v[12:13], v[12:13], v[22:23]
	v_pk_add_f32 v[24:25], v[10:11], v[24:25]
	ds_bpermute_b32 v9, v33, v4
	ds_bpermute_b32 v22, v33, v12
	ds_bpermute_b32 v23, v33, v13
	ds_bpermute_b32 v38, v33, v24
	ds_bpermute_b32 v39, v33, v25
	s_waitcnt lgkmcnt(4)
	v_add_f32_e32 v4, v4, v9
	ds_bpermute_b32 v9, v34, v4
	s_waitcnt lgkmcnt(3)
	v_pk_add_f32 v[10:11], v[12:13], v[22:23]
	ds_bpermute_b32 v16, v34, v14
	s_waitcnt lgkmcnt(2)
	v_pk_add_f32 v[22:23], v[24:25], v[38:39]
	ds_bpermute_b32 v17, v34, v15
	ds_bpermute_b32 v20, v34, v18
	ds_bpermute_b32 v21, v34, v19
	ds_bpermute_b32 v12, v34, v10
	ds_bpermute_b32 v13, v34, v11
	ds_bpermute_b32 v24, v34, v22
	ds_bpermute_b32 v25, v34, v23
	s_and_saveexec_b64 s[12:13], s[0:1]
	s_cbranch_execz .LBB0_92
	s_waitcnt lgkmcnt(8)
	v_add_f32_e32 v4, v4, v9
	v_fmamk_f32 v4, v4, 0x3a800000, v28
	s_mov_b32 s4, 0x800000
	v_mul_f32_e32 v9, 0x4b800000, v4
	v_cmp_gt_f32_e64 s[4:5], s4, v4
	s_waitcnt lgkmcnt(6)
	v_pk_add_f32 v[14:15], v[14:15], v[16:17]
	s_waitcnt lgkmcnt(4)
	v_pk_add_f32 v[16:17], v[18:19], v[20:21]
	v_cndmask_b32_e64 v4, v4, v9, s[4:5]
	v_rsq_f32_e32 v4, v4
	v_ashrrev_i32_e32 v9, 31, v8
	v_lshlrev_b64 v[38:39], 5, v[8:9]
	s_waitcnt lgkmcnt(2)
	v_pk_add_f32 v[10:11], v[10:11], v[12:13]
	v_mul_f32_e32 v37, 0x45800000, v4
	v_cndmask_b32_e64 v4, v4, v37, s[4:5]
	s_waitcnt lgkmcnt(0)
	v_pk_add_f32 v[12:13], v[22:23], v[24:25]
	v_lshl_add_u64 v[38:39], s[6:7], 0, v[38:39]
	v_pk_mul_f32 v[14:15], v[14:15], v[4:5] op_sel_hi:[1,0]
	v_pk_mul_f32 v[16:17], v[4:5], v[16:17] op_sel_hi:[0,1]
	v_pk_mul_f32 v[10:11], v[4:5], v[10:11] op_sel_hi:[0,1]
	v_pk_mul_f32 v[12:13], v[4:5], v[12:13] op_sel_hi:[0,1]
	v_lshl_add_u64 v[8:9], v[8:9], 2, s[90:91]
	global_store_dwordx4 v[38:39], v[14:17], off
	global_store_dwordx4 v[38:39], v[10:13], off offset:16
	global_store_dword v[8:9], v4, off
	s_branch .LBB0_92
